# v16 + residual GEMM epilogues (PH3, PH13): row sum-of-squares cross-lane reduction via v_permlane16_swap / v_permlane32_swap instead of two ds_bpermute LDS round trips
# baseline (speedup 1.0000x reference)
.LBB0_983:
	v_lshl_add_u32 v146, s28, 8, v148
	v_ashrrev_i32_e32 v147, 31, v146
	v_lshl_or_b32 v144, s30, 8, v150
	v_lshlrev_b64 v[156:157], 11, v[146:147]
	v_ashrrev_i32_e32 v145, 31, v144
	v_lshl_add_u64 v[156:157], s[14:15], 0, v[156:157]
	v_lshl_add_u64 v[166:167], v[144:145], 1, v[156:157]
	flat_load_dwordx4 v[158:161], v[166:167]
	flat_load_dwordx4 v[162:165], v[166:167] offset:256
	v_and_b32_e32 v156, 64, v154
	v_xor_b32_e32 v155, 16, v154
	v_add_u32_e32 v156, 64, v156
	v_xor_b32_e32 v157, 32, v154
	v_cmp_lt_i32_e32 vcc, v155, v156
	s_waitcnt vmcnt(0) lgkmcnt(0)
	v_lshlrev_b32_e32 v168, 16, v158
	v_cndmask_b32_e32 v155, v154, v155, vcc
	v_cmp_lt_i32_e32 vcc, v157, v156
	v_and_b32_e32 v169, 0xffff0000, v158
	v_lshlrev_b32_e32 v158, 16, v159
	v_and_b32_e32 v159, 0xffff0000, v159
	v_lshlrev_b32_e32 v170, 16, v160
	v_and_b32_e32 v171, 0xffff0000, v160
	v_lshlrev_b32_e32 v160, 16, v161
	v_and_b32_e32 v161, 0xffff0000, v161
	v_lshlrev_b32_e32 v172, 16, v162
	v_and_b32_e32 v173, 0xffff0000, v162
	v_lshlrev_b32_e32 v162, 16, v163
	v_and_b32_e32 v163, 0xffff0000, v163
	v_lshlrev_b32_e32 v174, 16, v164
	v_and_b32_e32 v175, 0xffff0000, v164
	v_lshlrev_b32_e32 v164, 16, v165
	v_and_b32_e32 v165, 0xffff0000, v165
	v_cndmask_b32_e32 v157, v154, v157, vcc
	v_pk_add_f32 v[126:127], v[126:127], v[158:159]
	v_pk_add_f32 v[124:125], v[124:125], v[168:169]
	v_pk_add_f32 v[122:123], v[122:123], v[160:161]
	v_pk_add_f32 v[120:121], v[120:121], v[170:171]
	v_pk_add_f32 v[118:119], v[118:119], v[162:163]
	v_pk_add_f32 v[116:117], v[116:117], v[172:173]
	v_pk_add_f32 v[158:159], v[114:115], v[164:165]
	v_pk_add_f32 v[160:161], v[112:113], v[174:175]
	v_lshlrev_b32_e32 v156, 2, v155
	v_lshlrev_b32_e32 v155, 2, v157
	v_cvt_pk_bf16_f32 v112, v124, v125
	v_cvt_pk_bf16_f32 v113, v126, v127
	v_mul_f32_e32 v114, v125, v125
	v_mul_f32_e32 v115, v127, v127
	v_mul_f32_e32 v125, v121, v121
	v_mul_f32_e32 v127, v123, v123
	v_mul_f32_e32 v157, v117, v117
	v_mul_f32_e32 v162, v119, v119
	v_mul_f32_e32 v163, v161, v161
	v_mul_f32_e32 v164, v159, v159
	v_fmac_f32_e32 v114, v124, v124
	v_fmac_f32_e32 v115, v126, v126
	v_fmac_f32_e32 v125, v120, v120
	v_fmac_f32_e32 v127, v122, v122
	v_fmac_f32_e32 v157, v116, v116
	v_fmac_f32_e32 v162, v118, v118
	v_fmac_f32_e32 v163, v160, v160
	v_fmac_f32_e32 v164, v158, v158
	v_add_f32_e32 v114, v114, v115
	v_add_f32_e32 v115, v125, v127
	v_add_f32_e32 v124, v157, v162
	v_add_f32_e32 v125, v163, v164
	v_add_f32_e32 v114, v114, v115
	v_add_f32_e32 v115, v124, v125
	v_add_f32_e32 v124, v114, v115
	v_mov_b32_e32 v125, v124
	v_cvt_pk_bf16_f32 v114, v120, v121
	v_cvt_pk_bf16_f32 v115, v122, v123
	flat_store_dwordx4 v[166:167], v[112:115]
	v_permlane16_swap_b32_e32 v124, v125
	s_nop 0
	v_add_f32_e32 v112, v124, v125
	v_mov_b32_e32 v113, v112
	v_cvt_pk_bf16_f32 v114, v116, v117
	v_cvt_pk_bf16_f32 v115, v118, v119
	v_cvt_pk_bf16_f32 v116, v160, v161
	v_cvt_pk_bf16_f32 v117, v158, v159
	flat_store_dwordx4 v[166:167], v[114:117] offset:256
	v_permlane32_swap_b32_e32 v112, v113
	s_and_saveexec_b64 s[28:29], s[4:5]
	s_cbranch_execz .LBB0_985
	v_lshl_add_u64 v[114:115], v[146:147], 2, s[12:13]
	s_nop 0
	v_add_f32_e32 v112, v112, v113
	flat_atomic_add_f32 v[114:115], v112
.LBB0_985:
	s_or_b64 exec, exec, s[28:29]
	v_or_b32_e32 v112, 16, v146
	s_waitcnt lgkmcnt(0)
	v_ashrrev_i32_e32 v113, 31, v112
	v_lshlrev_b64 v[114:115], 11, v[112:113]
	v_lshl_add_u64 v[114:115], s[14:15], 0, v[114:115]
	v_lshl_add_u64 v[122:123], v[144:145], 1, v[114:115]
	flat_load_dwordx4 v[114:117], v[122:123]
	flat_load_dwordx4 v[118:121], v[122:123] offset:256
	s_waitcnt vmcnt(0) lgkmcnt(0)
	v_lshlrev_b32_e32 v124, 16, v114
	v_and_b32_e32 v125, 0xffff0000, v114
	v_lshlrev_b32_e32 v114, 16, v115
	v_and_b32_e32 v115, 0xffff0000, v115
	v_lshlrev_b32_e32 v126, 16, v116
	v_and_b32_e32 v127, 0xffff0000, v116
	v_lshlrev_b32_e32 v116, 16, v117
	v_and_b32_e32 v117, 0xffff0000, v117
	v_lshlrev_b32_e32 v158, 16, v118
	v_and_b32_e32 v159, 0xffff0000, v118
	v_lshlrev_b32_e32 v118, 16, v119
	v_and_b32_e32 v119, 0xffff0000, v119
	v_lshlrev_b32_e32 v160, 16, v120
	v_and_b32_e32 v161, 0xffff0000, v120
	v_lshlrev_b32_e32 v120, 16, v121
	v_and_b32_e32 v121, 0xffff0000, v121
	v_pk_add_f32 v[110:111], v[110:111], v[114:115]
	v_pk_add_f32 v[108:109], v[108:109], v[124:125]
	v_pk_add_f32 v[106:107], v[106:107], v[116:117]
	v_pk_add_f32 v[104:105], v[104:105], v[126:127]
	v_pk_add_f32 v[102:103], v[102:103], v[118:119]
	v_pk_add_f32 v[100:101], v[100:101], v[158:159]
	v_pk_add_f32 v[114:115], v[98:99], v[120:121]
	v_pk_add_f32 v[116:117], v[96:97], v[160:161]
	v_cvt_pk_bf16_f32 v96, v108, v109
	v_cvt_pk_bf16_f32 v97, v110, v111
	v_mul_f32_e32 v98, v109, v109
	v_mul_f32_e32 v99, v111, v111
	v_mul_f32_e32 v109, v105, v105
	v_mul_f32_e32 v111, v107, v107
	v_mul_f32_e32 v118, v101, v101
	v_mul_f32_e32 v119, v103, v103
	v_mul_f32_e32 v120, v117, v117
	v_mul_f32_e32 v121, v115, v115
	v_fmac_f32_e32 v98, v108, v108
	v_fmac_f32_e32 v99, v110, v110
	v_fmac_f32_e32 v109, v104, v104
	v_fmac_f32_e32 v111, v106, v106
	v_fmac_f32_e32 v118, v100, v100
	v_fmac_f32_e32 v119, v102, v102
	v_fmac_f32_e32 v120, v116, v116
	v_fmac_f32_e32 v121, v114, v114
	v_add_f32_e32 v98, v98, v99
	v_add_f32_e32 v99, v109, v111
	v_add_f32_e32 v108, v118, v119
	v_add_f32_e32 v109, v120, v121
	v_add_f32_e32 v98, v98, v99
	v_add_f32_e32 v99, v108, v109
	v_add_f32_e32 v108, v98, v99
	v_mov_b32_e32 v109, v108
	v_cvt_pk_bf16_f32 v98, v104, v105
	v_cvt_pk_bf16_f32 v99, v106, v107
	flat_store_dwordx4 v[122:123], v[96:99]
	v_permlane16_swap_b32_e32 v108, v109
	s_nop 0
	v_add_f32_e32 v96, v108, v109
	v_mov_b32_e32 v97, v96
	v_cvt_pk_bf16_f32 v98, v100, v101
	v_cvt_pk_bf16_f32 v99, v102, v103
	v_cvt_pk_bf16_f32 v100, v116, v117
	v_cvt_pk_bf16_f32 v101, v114, v115
	flat_store_dwordx4 v[122:123], v[98:101] offset:256
	v_permlane32_swap_b32_e32 v96, v97
	s_and_saveexec_b64 s[28:29], s[4:5]
	s_cbranch_execz .LBB0_987
	v_lshl_add_u64 v[98:99], v[112:113], 2, s[12:13]
	s_nop 0
	v_add_f32_e32 v96, v96, v97
	flat_atomic_add_f32 v[98:99], v96
.LBB0_987:
	s_or_b64 exec, exec, s[28:29]
	v_or_b32_e32 v96, 32, v146
	s_waitcnt lgkmcnt(0)
	v_ashrrev_i32_e32 v97, 31, v96
	v_lshlrev_b64 v[98:99], 11, v[96:97]
	v_lshl_add_u64 v[98:99], s[14:15], 0, v[98:99]
	v_lshl_add_u64 v[106:107], v[144:145], 1, v[98:99]
	flat_load_dwordx4 v[98:101], v[106:107]
	flat_load_dwordx4 v[102:105], v[106:107] offset:256
	s_waitcnt vmcnt(0) lgkmcnt(0)
	v_lshlrev_b32_e32 v108, 16, v98
	v_and_b32_e32 v109, 0xffff0000, v98
	v_lshlrev_b32_e32 v98, 16, v99
	v_and_b32_e32 v99, 0xffff0000, v99
	v_lshlrev_b32_e32 v110, 16, v100
	v_and_b32_e32 v111, 0xffff0000, v100
	v_lshlrev_b32_e32 v100, 16, v101
	v_and_b32_e32 v101, 0xffff0000, v101
	v_lshlrev_b32_e32 v112, 16, v102
	v_and_b32_e32 v113, 0xffff0000, v102
	v_lshlrev_b32_e32 v102, 16, v103
	v_and_b32_e32 v103, 0xffff0000, v103
	v_lshlrev_b32_e32 v114, 16, v104
	v_and_b32_e32 v115, 0xffff0000, v104
	v_lshlrev_b32_e32 v104, 16, v105
	v_and_b32_e32 v105, 0xffff0000, v105
	v_pk_add_f32 v[94:95], v[94:95], v[98:99]
	v_pk_add_f32 v[92:93], v[92:93], v[108:109]
	v_pk_add_f32 v[90:91], v[90:91], v[100:101]
	v_pk_add_f32 v[88:89], v[88:89], v[110:111]
	v_pk_add_f32 v[86:87], v[86:87], v[102:103]
	v_pk_add_f32 v[84:85], v[84:85], v[112:113]
	v_pk_add_f32 v[98:99], v[82:83], v[104:105]
	v_pk_add_f32 v[100:101], v[80:81], v[114:115]
	v_cvt_pk_bf16_f32 v80, v92, v93
	v_cvt_pk_bf16_f32 v81, v94, v95
	v_mul_f32_e32 v82, v93, v93
	v_mul_f32_e32 v83, v95, v95
	v_mul_f32_e32 v93, v89, v89
	v_mul_f32_e32 v95, v91, v91
	v_mul_f32_e32 v102, v85, v85
	v_mul_f32_e32 v103, v87, v87
	v_mul_f32_e32 v104, v101, v101
	v_mul_f32_e32 v105, v99, v99
	v_fmac_f32_e32 v82, v92, v92
	v_fmac_f32_e32 v83, v94, v94
	v_fmac_f32_e32 v93, v88, v88
	v_fmac_f32_e32 v95, v90, v90
	v_fmac_f32_e32 v102, v84, v84
	v_fmac_f32_e32 v103, v86, v86
	v_fmac_f32_e32 v104, v100, v100
	v_fmac_f32_e32 v105, v98, v98
	v_add_f32_e32 v82, v82, v83
	v_add_f32_e32 v83, v93, v95
	v_add_f32_e32 v92, v102, v103
	v_add_f32_e32 v93, v104, v105
	v_add_f32_e32 v82, v82, v83
	v_add_f32_e32 v83, v92, v93
	v_add_f32_e32 v92, v82, v83
	v_mov_b32_e32 v93, v92
	v_cvt_pk_bf16_f32 v82, v88, v89
	v_cvt_pk_bf16_f32 v83, v90, v91
	flat_store_dwordx4 v[106:107], v[80:83]
	v_permlane16_swap_b32_e32 v92, v93
	s_nop 0
	v_add_f32_e32 v80, v92, v93
	v_mov_b32_e32 v81, v80
	v_cvt_pk_bf16_f32 v82, v84, v85
	v_cvt_pk_bf16_f32 v83, v86, v87
	v_cvt_pk_bf16_f32 v84, v100, v101
	v_cvt_pk_bf16_f32 v85, v98, v99
	flat_store_dwordx4 v[106:107], v[82:85] offset:256
	v_permlane32_swap_b32_e32 v80, v81
	s_and_saveexec_b64 s[28:29], s[4:5]
	s_cbranch_execz .LBB0_989
	v_lshl_add_u64 v[82:83], v[96:97], 2, s[12:13]
	s_nop 0
	v_add_f32_e32 v80, v80, v81
	flat_atomic_add_f32 v[82:83], v80
.LBB0_989:
	s_or_b64 exec, exec, s[28:29]
	v_or_b32_e32 v80, 48, v146
	s_waitcnt lgkmcnt(0)
	v_ashrrev_i32_e32 v81, 31, v80
	v_lshlrev_b64 v[82:83], 11, v[80:81]
	v_lshl_add_u64 v[82:83], s[14:15], 0, v[82:83]
	v_lshl_add_u64 v[90:91], v[144:145], 1, v[82:83]
	flat_load_dwordx4 v[82:85], v[90:91]
	flat_load_dwordx4 v[86:89], v[90:91] offset:256
	s_waitcnt vmcnt(0) lgkmcnt(0)
	v_lshlrev_b32_e32 v92, 16, v82
	v_and_b32_e32 v93, 0xffff0000, v82
	v_lshlrev_b32_e32 v82, 16, v83
	v_and_b32_e32 v83, 0xffff0000, v83
	v_lshlrev_b32_e32 v94, 16, v84
	v_and_b32_e32 v95, 0xffff0000, v84
	v_lshlrev_b32_e32 v84, 16, v85
	v_and_b32_e32 v85, 0xffff0000, v85
	v_lshlrev_b32_e32 v96, 16, v86
	v_and_b32_e32 v97, 0xffff0000, v86
	v_lshlrev_b32_e32 v86, 16, v87
	v_and_b32_e32 v87, 0xffff0000, v87
	v_lshlrev_b32_e32 v98, 16, v88
	v_and_b32_e32 v99, 0xffff0000, v88
	v_lshlrev_b32_e32 v88, 16, v89
	v_and_b32_e32 v89, 0xffff0000, v89
	v_pk_add_f32 v[78:79], v[78:79], v[82:83]
	v_pk_add_f32 v[76:77], v[76:77], v[92:93]
	v_pk_add_f32 v[74:75], v[74:75], v[84:85]
	v_pk_add_f32 v[72:73], v[72:73], v[94:95]
	v_pk_add_f32 v[70:71], v[70:71], v[86:87]
	v_pk_add_f32 v[68:69], v[68:69], v[96:97]
	v_pk_add_f32 v[82:83], v[66:67], v[88:89]
	v_pk_add_f32 v[84:85], v[64:65], v[98:99]
	v_cvt_pk_bf16_f32 v64, v76, v77
	v_cvt_pk_bf16_f32 v65, v78, v79
	v_mul_f32_e32 v66, v77, v77
	v_mul_f32_e32 v67, v79, v79
	v_mul_f32_e32 v77, v73, v73
	v_mul_f32_e32 v79, v75, v75
	v_mul_f32_e32 v86, v69, v69
	v_mul_f32_e32 v87, v71, v71
	v_mul_f32_e32 v88, v85, v85
	v_mul_f32_e32 v89, v83, v83
	v_fmac_f32_e32 v66, v76, v76
	v_fmac_f32_e32 v67, v78, v78
	v_fmac_f32_e32 v77, v72, v72
	v_fmac_f32_e32 v79, v74, v74
	v_fmac_f32_e32 v86, v68, v68
	v_fmac_f32_e32 v87, v70, v70
	v_fmac_f32_e32 v88, v84, v84
	v_fmac_f32_e32 v89, v82, v82
	v_add_f32_e32 v66, v66, v67
	v_add_f32_e32 v67, v77, v79
	v_add_f32_e32 v76, v86, v87
	v_add_f32_e32 v77, v88, v89
	v_add_f32_e32 v66, v66, v67
	v_add_f32_e32 v67, v76, v77
	v_add_f32_e32 v76, v66, v67
	v_mov_b32_e32 v77, v76
	v_cvt_pk_bf16_f32 v66, v72, v73
	v_cvt_pk_bf16_f32 v67, v74, v75
	flat_store_dwordx4 v[90:91], v[64:67]
	v_permlane16_swap_b32_e32 v76, v77
	s_nop 0
	v_add_f32_e32 v64, v76, v77
	v_mov_b32_e32 v65, v64
	v_cvt_pk_bf16_f32 v66, v68, v69
	v_cvt_pk_bf16_f32 v67, v70, v71
	v_cvt_pk_bf16_f32 v68, v84, v85
	v_cvt_pk_bf16_f32 v69, v82, v83
	flat_store_dwordx4 v[90:91], v[66:69] offset:256
	v_permlane32_swap_b32_e32 v64, v65
	s_and_saveexec_b64 s[28:29], s[4:5]
	s_cbranch_execz .LBB0_991
	v_lshl_add_u64 v[66:67], v[80:81], 2, s[12:13]
	s_nop 0
	v_add_f32_e32 v64, v64, v65
	flat_atomic_add_f32 v[66:67], v64
.LBB0_991:
	s_or_b64 exec, exec, s[28:29]
	v_add_u32_e32 v64, 0x80, v146
	s_waitcnt lgkmcnt(0)
	v_ashrrev_i32_e32 v65, 31, v64
	v_lshlrev_b64 v[66:67], 11, v[64:65]
	v_lshl_add_u64 v[66:67], s[14:15], 0, v[66:67]
	v_lshl_add_u64 v[74:75], v[144:145], 1, v[66:67]
	flat_load_dwordx4 v[66:69], v[74:75]
	flat_load_dwordx4 v[70:73], v[74:75] offset:256
	s_waitcnt vmcnt(0) lgkmcnt(0)
	v_lshlrev_b32_e32 v76, 16, v66
	v_and_b32_e32 v77, 0xffff0000, v66
	v_lshlrev_b32_e32 v66, 16, v67
	v_and_b32_e32 v67, 0xffff0000, v67
	v_lshlrev_b32_e32 v78, 16, v68
	v_and_b32_e32 v79, 0xffff0000, v68
	v_lshlrev_b32_e32 v68, 16, v69
	v_and_b32_e32 v69, 0xffff0000, v69
	v_lshlrev_b32_e32 v80, 16, v70
	v_and_b32_e32 v81, 0xffff0000, v70
	v_lshlrev_b32_e32 v70, 16, v71
	v_and_b32_e32 v71, 0xffff0000, v71
	v_lshlrev_b32_e32 v82, 16, v72
	v_and_b32_e32 v83, 0xffff0000, v72
	v_lshlrev_b32_e32 v72, 16, v73
	v_and_b32_e32 v73, 0xffff0000, v73
	v_pk_add_f32 v[62:63], v[62:63], v[66:67]
	v_pk_add_f32 v[60:61], v[60:61], v[76:77]
	v_pk_add_f32 v[58:59], v[58:59], v[68:69]
	v_pk_add_f32 v[56:57], v[56:57], v[78:79]
	v_pk_add_f32 v[54:55], v[54:55], v[70:71]
	v_pk_add_f32 v[52:53], v[52:53], v[80:81]
	v_pk_add_f32 v[66:67], v[50:51], v[72:73]
	v_pk_add_f32 v[68:69], v[48:49], v[82:83]
	v_cvt_pk_bf16_f32 v48, v60, v61
	v_cvt_pk_bf16_f32 v49, v62, v63
	v_mul_f32_e32 v50, v61, v61
	v_mul_f32_e32 v51, v63, v63
	v_mul_f32_e32 v61, v57, v57
	v_mul_f32_e32 v63, v59, v59
	v_mul_f32_e32 v70, v53, v53
	v_mul_f32_e32 v71, v55, v55
	v_mul_f32_e32 v72, v69, v69
	v_mul_f32_e32 v73, v67, v67
	v_fmac_f32_e32 v50, v60, v60
	v_fmac_f32_e32 v51, v62, v62
	v_fmac_f32_e32 v61, v56, v56
	v_fmac_f32_e32 v63, v58, v58
	v_fmac_f32_e32 v70, v52, v52
	v_fmac_f32_e32 v71, v54, v54
	v_fmac_f32_e32 v72, v68, v68
	v_fmac_f32_e32 v73, v66, v66
	v_add_f32_e32 v50, v50, v51
	v_add_f32_e32 v51, v61, v63
	v_add_f32_e32 v60, v70, v71
	v_add_f32_e32 v61, v72, v73
	v_add_f32_e32 v50, v50, v51
	v_add_f32_e32 v51, v60, v61
	v_add_f32_e32 v60, v50, v51
	v_mov_b32_e32 v61, v60
	v_cvt_pk_bf16_f32 v50, v56, v57
	v_cvt_pk_bf16_f32 v51, v58, v59
	flat_store_dwordx4 v[74:75], v[48:51]
	v_permlane16_swap_b32_e32 v60, v61
	s_nop 0
	v_add_f32_e32 v48, v60, v61
	v_mov_b32_e32 v49, v48
	v_cvt_pk_bf16_f32 v50, v52, v53
	v_cvt_pk_bf16_f32 v51, v54, v55
	v_cvt_pk_bf16_f32 v52, v68, v69
	v_cvt_pk_bf16_f32 v53, v66, v67
	flat_store_dwordx4 v[74:75], v[50:53] offset:256
	v_permlane32_swap_b32_e32 v48, v49
	s_and_saveexec_b64 s[28:29], s[4:5]
	s_cbranch_execz .LBB0_993
	v_lshl_add_u64 v[50:51], v[64:65], 2, s[12:13]
	s_nop 0
	v_add_f32_e32 v48, v48, v49
	flat_atomic_add_f32 v[50:51], v48
.LBB0_993:
	s_or_b64 exec, exec, s[28:29]
	v_add_u32_e32 v48, 0x90, v146
	s_waitcnt lgkmcnt(0)
	v_ashrrev_i32_e32 v49, 31, v48
	v_lshlrev_b64 v[50:51], 11, v[48:49]
	v_lshl_add_u64 v[50:51], s[14:15], 0, v[50:51]
	v_lshl_add_u64 v[58:59], v[144:145], 1, v[50:51]
	flat_load_dwordx4 v[50:53], v[58:59]
	flat_load_dwordx4 v[54:57], v[58:59] offset:256
	s_waitcnt vmcnt(0) lgkmcnt(0)
	v_lshlrev_b32_e32 v60, 16, v50
	v_and_b32_e32 v61, 0xffff0000, v50
	v_lshlrev_b32_e32 v50, 16, v51
	v_and_b32_e32 v51, 0xffff0000, v51
	v_lshlrev_b32_e32 v62, 16, v52
	v_and_b32_e32 v63, 0xffff0000, v52
	v_lshlrev_b32_e32 v52, 16, v53
	v_and_b32_e32 v53, 0xffff0000, v53
	v_lshlrev_b32_e32 v64, 16, v54
	v_and_b32_e32 v65, 0xffff0000, v54
	v_lshlrev_b32_e32 v54, 16, v55
	v_and_b32_e32 v55, 0xffff0000, v55
	v_lshlrev_b32_e32 v66, 16, v56
	v_and_b32_e32 v67, 0xffff0000, v56
	v_lshlrev_b32_e32 v56, 16, v57
	v_and_b32_e32 v57, 0xffff0000, v57
	v_pk_add_f32 v[46:47], v[46:47], v[50:51]
	v_pk_add_f32 v[44:45], v[44:45], v[60:61]
	v_pk_add_f32 v[42:43], v[42:43], v[52:53]
	v_pk_add_f32 v[40:41], v[40:41], v[62:63]
	v_pk_add_f32 v[38:39], v[38:39], v[54:55]
	v_pk_add_f32 v[36:37], v[36:37], v[64:65]
	v_pk_add_f32 v[50:51], v[34:35], v[56:57]
	v_pk_add_f32 v[52:53], v[32:33], v[66:67]
	v_cvt_pk_bf16_f32 v32, v44, v45
	v_cvt_pk_bf16_f32 v33, v46, v47
	v_mul_f32_e32 v34, v45, v45
	v_mul_f32_e32 v35, v47, v47
	v_mul_f32_e32 v45, v41, v41
	v_mul_f32_e32 v47, v43, v43
	v_mul_f32_e32 v54, v37, v37
	v_mul_f32_e32 v55, v39, v39
	v_mul_f32_e32 v56, v53, v53
	v_mul_f32_e32 v57, v51, v51
	v_fmac_f32_e32 v34, v44, v44
	v_fmac_f32_e32 v35, v46, v46
	v_fmac_f32_e32 v45, v40, v40
	v_fmac_f32_e32 v47, v42, v42
	v_fmac_f32_e32 v54, v36, v36
	v_fmac_f32_e32 v55, v38, v38
	v_fmac_f32_e32 v56, v52, v52
	v_fmac_f32_e32 v57, v50, v50
	v_add_f32_e32 v34, v34, v35
	v_add_f32_e32 v35, v45, v47
	v_add_f32_e32 v44, v54, v55
	v_add_f32_e32 v45, v56, v57
	v_add_f32_e32 v34, v34, v35
	v_add_f32_e32 v35, v44, v45
	v_add_f32_e32 v44, v34, v35
	v_mov_b32_e32 v45, v44
	v_cvt_pk_bf16_f32 v34, v40, v41
	v_cvt_pk_bf16_f32 v35, v42, v43
	flat_store_dwordx4 v[58:59], v[32:35]
	v_permlane16_swap_b32_e32 v44, v45
	s_nop 0
	v_add_f32_e32 v32, v44, v45
	v_mov_b32_e32 v33, v32
	v_cvt_pk_bf16_f32 v34, v36, v37
	v_cvt_pk_bf16_f32 v35, v38, v39
	v_cvt_pk_bf16_f32 v36, v52, v53
	v_cvt_pk_bf16_f32 v37, v50, v51
	flat_store_dwordx4 v[58:59], v[34:37] offset:256
	v_permlane32_swap_b32_e32 v32, v33
	s_and_saveexec_b64 s[28:29], s[4:5]
	s_cbranch_execz .LBB0_995
	v_lshl_add_u64 v[34:35], v[48:49], 2, s[12:13]
	s_nop 0
	v_add_f32_e32 v32, v32, v33
	flat_atomic_add_f32 v[34:35], v32
.LBB0_995:
	s_or_b64 exec, exec, s[28:29]
	v_add_u32_e32 v32, 0xa0, v146
	s_waitcnt lgkmcnt(0)
	v_ashrrev_i32_e32 v33, 31, v32
	v_lshlrev_b64 v[34:35], 11, v[32:33]
	v_lshl_add_u64 v[34:35], s[14:15], 0, v[34:35]
	v_lshl_add_u64 v[42:43], v[144:145], 1, v[34:35]
	flat_load_dwordx4 v[34:37], v[42:43]
	flat_load_dwordx4 v[38:41], v[42:43] offset:256
	s_waitcnt vmcnt(0) lgkmcnt(0)
	v_lshlrev_b32_e32 v44, 16, v34
	v_and_b32_e32 v45, 0xffff0000, v34
	v_lshlrev_b32_e32 v34, 16, v35
	v_and_b32_e32 v35, 0xffff0000, v35
	v_lshlrev_b32_e32 v46, 16, v36
	v_and_b32_e32 v47, 0xffff0000, v36
	v_lshlrev_b32_e32 v36, 16, v37
	v_and_b32_e32 v37, 0xffff0000, v37
	v_lshlrev_b32_e32 v48, 16, v38
	v_and_b32_e32 v49, 0xffff0000, v38
	v_lshlrev_b32_e32 v38, 16, v39
	v_and_b32_e32 v39, 0xffff0000, v39
	v_lshlrev_b32_e32 v50, 16, v40
	v_and_b32_e32 v51, 0xffff0000, v40
	v_lshlrev_b32_e32 v40, 16, v41
	v_and_b32_e32 v41, 0xffff0000, v41
	v_pk_add_f32 v[30:31], v[30:31], v[34:35]
	v_pk_add_f32 v[28:29], v[28:29], v[44:45]
	v_pk_add_f32 v[26:27], v[26:27], v[36:37]
	v_pk_add_f32 v[24:25], v[24:25], v[46:47]
	v_pk_add_f32 v[22:23], v[22:23], v[38:39]
	v_pk_add_f32 v[20:21], v[20:21], v[48:49]
	v_pk_add_f32 v[34:35], v[18:19], v[40:41]
	v_pk_add_f32 v[36:37], v[16:17], v[50:51]
	v_cvt_pk_bf16_f32 v16, v28, v29
	v_cvt_pk_bf16_f32 v17, v30, v31
	v_mul_f32_e32 v18, v29, v29
	v_mul_f32_e32 v19, v31, v31
	v_mul_f32_e32 v29, v25, v25
	v_mul_f32_e32 v31, v27, v27
	v_mul_f32_e32 v38, v21, v21
	v_mul_f32_e32 v39, v23, v23
	v_mul_f32_e32 v40, v37, v37
	v_mul_f32_e32 v41, v35, v35
	v_fmac_f32_e32 v18, v28, v28
	v_fmac_f32_e32 v19, v30, v30
	v_fmac_f32_e32 v29, v24, v24
	v_fmac_f32_e32 v31, v26, v26
	v_fmac_f32_e32 v38, v20, v20
	v_fmac_f32_e32 v39, v22, v22
	v_fmac_f32_e32 v40, v36, v36
	v_fmac_f32_e32 v41, v34, v34
	v_add_f32_e32 v18, v18, v19
	v_add_f32_e32 v19, v29, v31
	v_add_f32_e32 v28, v38, v39
	v_add_f32_e32 v29, v40, v41
	v_add_f32_e32 v18, v18, v19
	v_add_f32_e32 v19, v28, v29
	v_add_f32_e32 v28, v18, v19
	v_mov_b32_e32 v29, v28
	v_cvt_pk_bf16_f32 v18, v24, v25
	v_cvt_pk_bf16_f32 v19, v26, v27
	flat_store_dwordx4 v[42:43], v[16:19]
	v_permlane16_swap_b32_e32 v28, v29
	s_nop 0
	v_add_f32_e32 v16, v28, v29
	v_mov_b32_e32 v17, v16
	v_cvt_pk_bf16_f32 v18, v20, v21
	v_cvt_pk_bf16_f32 v19, v22, v23
	v_cvt_pk_bf16_f32 v20, v36, v37
	v_cvt_pk_bf16_f32 v21, v34, v35
	flat_store_dwordx4 v[42:43], v[18:21] offset:256
	v_permlane32_swap_b32_e32 v16, v17
	s_and_saveexec_b64 s[28:29], s[4:5]
	s_cbranch_execz .LBB0_997
	v_lshl_add_u64 v[18:19], v[32:33], 2, s[12:13]
	s_nop 0
	v_add_f32_e32 v16, v16, v17
	flat_atomic_add_f32 v[18:19], v16
.LBB0_997:
	s_or_b64 exec, exec, s[28:29]
	v_add_u32_e32 v16, 0xb0, v146
	s_waitcnt lgkmcnt(0)
	v_ashrrev_i32_e32 v17, 31, v16
	v_lshlrev_b64 v[18:19], 11, v[16:17]
	v_lshl_add_u64 v[18:19], s[14:15], 0, v[18:19]
	v_lshl_add_u64 v[26:27], v[144:145], 1, v[18:19]
	flat_load_dwordx4 v[18:21], v[26:27]
	flat_load_dwordx4 v[22:25], v[26:27] offset:256
	s_waitcnt vmcnt(0) lgkmcnt(0)
	v_lshlrev_b32_e32 v28, 16, v18
	v_and_b32_e32 v29, 0xffff0000, v18
	v_lshlrev_b32_e32 v18, 16, v19
	v_and_b32_e32 v19, 0xffff0000, v19
	v_lshlrev_b32_e32 v30, 16, v20
	v_and_b32_e32 v31, 0xffff0000, v20
	v_lshlrev_b32_e32 v20, 16, v21
	v_and_b32_e32 v21, 0xffff0000, v21
	v_lshlrev_b32_e32 v32, 16, v22
	v_and_b32_e32 v33, 0xffff0000, v22
	v_lshlrev_b32_e32 v22, 16, v23
	v_and_b32_e32 v23, 0xffff0000, v23
	v_lshlrev_b32_e32 v34, 16, v24
	v_and_b32_e32 v35, 0xffff0000, v24
	v_lshlrev_b32_e32 v24, 16, v25
	v_and_b32_e32 v25, 0xffff0000, v25
	v_pk_add_f32 v[14:15], v[14:15], v[18:19]
	v_pk_add_f32 v[12:13], v[12:13], v[28:29]
	v_pk_add_f32 v[10:11], v[10:11], v[20:21]
	v_pk_add_f32 v[8:9], v[8:9], v[30:31]
	v_pk_add_f32 v[6:7], v[6:7], v[22:23]
	v_pk_add_f32 v[4:5], v[4:5], v[32:33]
	v_pk_add_f32 v[18:19], v[2:3], v[24:25]
	v_pk_add_f32 v[20:21], v[0:1], v[34:35]
	v_cvt_pk_bf16_f32 v0, v12, v13
	v_cvt_pk_bf16_f32 v1, v14, v15
	v_mul_f32_e32 v2, v13, v13
	v_mul_f32_e32 v3, v15, v15
	v_mul_f32_e32 v13, v9, v9
	v_mul_f32_e32 v15, v11, v11
	v_mul_f32_e32 v22, v5, v5
	v_mul_f32_e32 v23, v7, v7
	v_mul_f32_e32 v24, v21, v21
	v_mul_f32_e32 v25, v19, v19
	v_fmac_f32_e32 v2, v12, v12
	v_fmac_f32_e32 v3, v14, v14
	v_fmac_f32_e32 v13, v8, v8
	v_fmac_f32_e32 v15, v10, v10
	v_fmac_f32_e32 v22, v4, v4
	v_fmac_f32_e32 v23, v6, v6
	v_fmac_f32_e32 v24, v20, v20
	v_fmac_f32_e32 v25, v18, v18
	v_add_f32_e32 v2, v2, v3
	v_add_f32_e32 v3, v13, v15
	v_add_f32_e32 v12, v22, v23
	v_add_f32_e32 v13, v24, v25
	v_add_f32_e32 v2, v2, v3
	v_add_f32_e32 v3, v12, v13
	v_add_f32_e32 v12, v2, v3
	v_mov_b32_e32 v13, v12
	v_cvt_pk_bf16_f32 v2, v8, v9
	v_cvt_pk_bf16_f32 v3, v10, v11
	flat_store_dwordx4 v[26:27], v[0:3]
	v_permlane16_swap_b32_e32 v12, v13
	s_nop 0
	v_add_f32_e32 v0, v12, v13
	v_mov_b32_e32 v1, v0
	v_cvt_pk_bf16_f32 v2, v4, v5
	v_cvt_pk_bf16_f32 v3, v6, v7
	v_cvt_pk_bf16_f32 v4, v20, v21
	v_cvt_pk_bf16_f32 v5, v18, v19
	flat_store_dwordx4 v[26:27], v[2:5] offset:256
	v_permlane32_swap_b32_e32 v0, v1
	s_and_saveexec_b64 s[28:29], s[4:5]
	s_cbranch_execz .LBB0_999
	v_lshl_add_u64 v[2:3], v[16:17], 2, s[12:13]
	s_nop 0
	v_add_f32_e32 v0, v0, v1
	flat_atomic_add_f32 v[2:3], v0

.LBB0_1786:
	v_lshl_add_u32 v146, s26, 8, v148
	v_ashrrev_i32_e32 v147, 31, v146
	v_lshl_or_b32 v144, s24, 8, v150
	v_lshlrev_b64 v[156:157], 11, v[146:147]
	v_ashrrev_i32_e32 v145, 31, v144
	v_lshl_add_u64 v[156:157], s[6:7], 0, v[156:157]
	v_lshl_add_u64 v[166:167], v[144:145], 1, v[156:157]
	flat_load_dwordx4 v[158:161], v[166:167]
	flat_load_dwordx4 v[162:165], v[166:167] offset:256
	v_and_b32_e32 v156, 64, v154
	v_xor_b32_e32 v155, 16, v154
	v_add_u32_e32 v156, 64, v156
	v_xor_b32_e32 v157, 32, v154
	v_cmp_lt_i32_e32 vcc, v155, v156
	s_waitcnt vmcnt(0) lgkmcnt(0)
	v_lshlrev_b32_e32 v168, 16, v158
	v_cndmask_b32_e32 v155, v154, v155, vcc
	v_cmp_lt_i32_e32 vcc, v157, v156
	v_and_b32_e32 v169, 0xffff0000, v158
	v_lshlrev_b32_e32 v158, 16, v159
	v_and_b32_e32 v159, 0xffff0000, v159
	v_lshlrev_b32_e32 v170, 16, v160
	v_and_b32_e32 v171, 0xffff0000, v160
	v_lshlrev_b32_e32 v160, 16, v161
	v_and_b32_e32 v161, 0xffff0000, v161
	v_lshlrev_b32_e32 v172, 16, v162
	v_and_b32_e32 v173, 0xffff0000, v162
	v_lshlrev_b32_e32 v162, 16, v163
	v_and_b32_e32 v163, 0xffff0000, v163
	v_lshlrev_b32_e32 v174, 16, v164
	v_and_b32_e32 v175, 0xffff0000, v164
	v_lshlrev_b32_e32 v164, 16, v165
	v_and_b32_e32 v165, 0xffff0000, v165
	v_cndmask_b32_e32 v157, v154, v157, vcc
	v_pk_add_f32 v[126:127], v[126:127], v[158:159]
	v_pk_add_f32 v[124:125], v[124:125], v[168:169]
	v_pk_add_f32 v[122:123], v[122:123], v[160:161]
	v_pk_add_f32 v[120:121], v[120:121], v[170:171]
	v_pk_add_f32 v[118:119], v[118:119], v[162:163]
	v_pk_add_f32 v[116:117], v[116:117], v[172:173]
	v_pk_add_f32 v[158:159], v[114:115], v[164:165]
	v_pk_add_f32 v[160:161], v[112:113], v[174:175]
	v_lshlrev_b32_e32 v156, 2, v155
	v_lshlrev_b32_e32 v155, 2, v157
	v_cvt_pk_bf16_f32 v112, v124, v125
	v_cvt_pk_bf16_f32 v113, v126, v127
	v_mul_f32_e32 v114, v125, v125
	v_mul_f32_e32 v115, v127, v127
	v_mul_f32_e32 v125, v121, v121
	v_mul_f32_e32 v127, v123, v123
	v_mul_f32_e32 v157, v117, v117
	v_mul_f32_e32 v162, v119, v119
	v_mul_f32_e32 v163, v161, v161
	v_mul_f32_e32 v164, v159, v159
	v_fmac_f32_e32 v114, v124, v124
	v_fmac_f32_e32 v115, v126, v126
	v_fmac_f32_e32 v125, v120, v120
	v_fmac_f32_e32 v127, v122, v122
	v_fmac_f32_e32 v157, v116, v116
	v_fmac_f32_e32 v162, v118, v118
	v_fmac_f32_e32 v163, v160, v160
	v_fmac_f32_e32 v164, v158, v158
	v_add_f32_e32 v114, v114, v115
	v_add_f32_e32 v115, v125, v127
	v_add_f32_e32 v124, v157, v162
	v_add_f32_e32 v125, v163, v164
	v_add_f32_e32 v114, v114, v115
	v_add_f32_e32 v115, v124, v125
	v_add_f32_e32 v124, v114, v115
	v_mov_b32_e32 v125, v124
	v_cvt_pk_bf16_f32 v114, v120, v121
	v_cvt_pk_bf16_f32 v115, v122, v123
	flat_store_dwordx4 v[166:167], v[112:115]
	v_permlane16_swap_b32_e32 v124, v125
	s_nop 0
	v_add_f32_e32 v112, v124, v125
	v_mov_b32_e32 v113, v112
	v_cvt_pk_bf16_f32 v114, v116, v117
	v_cvt_pk_bf16_f32 v115, v118, v119
	v_cvt_pk_bf16_f32 v116, v160, v161
	v_cvt_pk_bf16_f32 v117, v158, v159
	flat_store_dwordx4 v[166:167], v[114:117] offset:256
	v_permlane32_swap_b32_e32 v112, v113
	s_and_saveexec_b64 s[24:25], s[0:1]
	s_cbranch_execz .LBB0_1788
	v_lshl_add_u64 v[114:115], v[146:147], 2, s[10:11]
	s_nop 0
	v_add_f32_e32 v112, v112, v113
	flat_atomic_add_f32 v[114:115], v112
.LBB0_1788:
	s_or_b64 exec, exec, s[24:25]
	v_or_b32_e32 v112, 16, v146
	s_waitcnt lgkmcnt(0)
	v_ashrrev_i32_e32 v113, 31, v112
	v_lshlrev_b64 v[114:115], 11, v[112:113]
	v_lshl_add_u64 v[114:115], s[6:7], 0, v[114:115]
	v_lshl_add_u64 v[122:123], v[144:145], 1, v[114:115]
	flat_load_dwordx4 v[114:117], v[122:123]
	flat_load_dwordx4 v[118:121], v[122:123] offset:256
	s_waitcnt vmcnt(0) lgkmcnt(0)
	v_lshlrev_b32_e32 v124, 16, v114
	v_and_b32_e32 v125, 0xffff0000, v114
	v_lshlrev_b32_e32 v114, 16, v115
	v_and_b32_e32 v115, 0xffff0000, v115
	v_lshlrev_b32_e32 v126, 16, v116
	v_and_b32_e32 v127, 0xffff0000, v116
	v_lshlrev_b32_e32 v116, 16, v117
	v_and_b32_e32 v117, 0xffff0000, v117
	v_lshlrev_b32_e32 v158, 16, v118
	v_and_b32_e32 v159, 0xffff0000, v118
	v_lshlrev_b32_e32 v118, 16, v119
	v_and_b32_e32 v119, 0xffff0000, v119
	v_lshlrev_b32_e32 v160, 16, v120
	v_and_b32_e32 v161, 0xffff0000, v120
	v_lshlrev_b32_e32 v120, 16, v121
	v_and_b32_e32 v121, 0xffff0000, v121
	v_pk_add_f32 v[110:111], v[110:111], v[114:115]
	v_pk_add_f32 v[108:109], v[108:109], v[124:125]
	v_pk_add_f32 v[106:107], v[106:107], v[116:117]
	v_pk_add_f32 v[104:105], v[104:105], v[126:127]
	v_pk_add_f32 v[102:103], v[102:103], v[118:119]
	v_pk_add_f32 v[100:101], v[100:101], v[158:159]
	v_pk_add_f32 v[114:115], v[98:99], v[120:121]
	v_pk_add_f32 v[116:117], v[96:97], v[160:161]
	v_cvt_pk_bf16_f32 v96, v108, v109
	v_cvt_pk_bf16_f32 v97, v110, v111
	v_mul_f32_e32 v98, v109, v109
	v_mul_f32_e32 v99, v111, v111
	v_mul_f32_e32 v109, v105, v105
	v_mul_f32_e32 v111, v107, v107
	v_mul_f32_e32 v118, v101, v101
	v_mul_f32_e32 v119, v103, v103
	v_mul_f32_e32 v120, v117, v117
	v_mul_f32_e32 v121, v115, v115
	v_fmac_f32_e32 v98, v108, v108
	v_fmac_f32_e32 v99, v110, v110
	v_fmac_f32_e32 v109, v104, v104
	v_fmac_f32_e32 v111, v106, v106
	v_fmac_f32_e32 v118, v100, v100
	v_fmac_f32_e32 v119, v102, v102
	v_fmac_f32_e32 v120, v116, v116
	v_fmac_f32_e32 v121, v114, v114
	v_add_f32_e32 v98, v98, v99
	v_add_f32_e32 v99, v109, v111
	v_add_f32_e32 v108, v118, v119
	v_add_f32_e32 v109, v120, v121
	v_add_f32_e32 v98, v98, v99
	v_add_f32_e32 v99, v108, v109
	v_add_f32_e32 v108, v98, v99
	v_mov_b32_e32 v109, v108
	v_cvt_pk_bf16_f32 v98, v104, v105
	v_cvt_pk_bf16_f32 v99, v106, v107
	flat_store_dwordx4 v[122:123], v[96:99]
	v_permlane16_swap_b32_e32 v108, v109
	s_nop 0
	v_add_f32_e32 v96, v108, v109
	v_mov_b32_e32 v97, v96
	v_cvt_pk_bf16_f32 v98, v100, v101
	v_cvt_pk_bf16_f32 v99, v102, v103
	v_cvt_pk_bf16_f32 v100, v116, v117
	v_cvt_pk_bf16_f32 v101, v114, v115
	flat_store_dwordx4 v[122:123], v[98:101] offset:256
	v_permlane32_swap_b32_e32 v96, v97
	s_and_saveexec_b64 s[24:25], s[0:1]
	s_cbranch_execz .LBB0_1790
	v_lshl_add_u64 v[98:99], v[112:113], 2, s[10:11]
	s_nop 0
	v_add_f32_e32 v96, v96, v97
	flat_atomic_add_f32 v[98:99], v96
.LBB0_1790:
	s_or_b64 exec, exec, s[24:25]
	v_or_b32_e32 v96, 32, v146
	s_waitcnt lgkmcnt(0)
	v_ashrrev_i32_e32 v97, 31, v96
	v_lshlrev_b64 v[98:99], 11, v[96:97]
	v_lshl_add_u64 v[98:99], s[6:7], 0, v[98:99]
	v_lshl_add_u64 v[106:107], v[144:145], 1, v[98:99]
	flat_load_dwordx4 v[98:101], v[106:107]
	flat_load_dwordx4 v[102:105], v[106:107] offset:256
	s_waitcnt vmcnt(0) lgkmcnt(0)
	v_lshlrev_b32_e32 v108, 16, v98
	v_and_b32_e32 v109, 0xffff0000, v98
	v_lshlrev_b32_e32 v98, 16, v99
	v_and_b32_e32 v99, 0xffff0000, v99
	v_lshlrev_b32_e32 v110, 16, v100
	v_and_b32_e32 v111, 0xffff0000, v100
	v_lshlrev_b32_e32 v100, 16, v101
	v_and_b32_e32 v101, 0xffff0000, v101
	v_lshlrev_b32_e32 v112, 16, v102
	v_and_b32_e32 v113, 0xffff0000, v102
	v_lshlrev_b32_e32 v102, 16, v103
	v_and_b32_e32 v103, 0xffff0000, v103
	v_lshlrev_b32_e32 v114, 16, v104
	v_and_b32_e32 v115, 0xffff0000, v104
	v_lshlrev_b32_e32 v104, 16, v105
	v_and_b32_e32 v105, 0xffff0000, v105
	v_pk_add_f32 v[94:95], v[94:95], v[98:99]
	v_pk_add_f32 v[92:93], v[92:93], v[108:109]
	v_pk_add_f32 v[90:91], v[90:91], v[100:101]
	v_pk_add_f32 v[88:89], v[88:89], v[110:111]
	v_pk_add_f32 v[86:87], v[86:87], v[102:103]
	v_pk_add_f32 v[84:85], v[84:85], v[112:113]
	v_pk_add_f32 v[98:99], v[82:83], v[104:105]
	v_pk_add_f32 v[100:101], v[80:81], v[114:115]
	v_cvt_pk_bf16_f32 v80, v92, v93
	v_cvt_pk_bf16_f32 v81, v94, v95
	v_mul_f32_e32 v82, v93, v93
	v_mul_f32_e32 v83, v95, v95
	v_mul_f32_e32 v93, v89, v89
	v_mul_f32_e32 v95, v91, v91
	v_mul_f32_e32 v102, v85, v85
	v_mul_f32_e32 v103, v87, v87
	v_mul_f32_e32 v104, v101, v101
	v_mul_f32_e32 v105, v99, v99
	v_fmac_f32_e32 v82, v92, v92
	v_fmac_f32_e32 v83, v94, v94
	v_fmac_f32_e32 v93, v88, v88
	v_fmac_f32_e32 v95, v90, v90
	v_fmac_f32_e32 v102, v84, v84
	v_fmac_f32_e32 v103, v86, v86
	v_fmac_f32_e32 v104, v100, v100
	v_fmac_f32_e32 v105, v98, v98
	v_add_f32_e32 v82, v82, v83
	v_add_f32_e32 v83, v93, v95
	v_add_f32_e32 v92, v102, v103
	v_add_f32_e32 v93, v104, v105
	v_add_f32_e32 v82, v82, v83
	v_add_f32_e32 v83, v92, v93
	v_add_f32_e32 v92, v82, v83
	v_mov_b32_e32 v93, v92
	v_cvt_pk_bf16_f32 v82, v88, v89
	v_cvt_pk_bf16_f32 v83, v90, v91
	flat_store_dwordx4 v[106:107], v[80:83]
	v_permlane16_swap_b32_e32 v92, v93
	s_nop 0
	v_add_f32_e32 v80, v92, v93
	v_mov_b32_e32 v81, v80
	v_cvt_pk_bf16_f32 v82, v84, v85
	v_cvt_pk_bf16_f32 v83, v86, v87
	v_cvt_pk_bf16_f32 v84, v100, v101
	v_cvt_pk_bf16_f32 v85, v98, v99
	flat_store_dwordx4 v[106:107], v[82:85] offset:256
	v_permlane32_swap_b32_e32 v80, v81
	s_and_saveexec_b64 s[24:25], s[0:1]
	s_cbranch_execz .LBB0_1792
	v_lshl_add_u64 v[82:83], v[96:97], 2, s[10:11]
	s_nop 0
	v_add_f32_e32 v80, v80, v81
	flat_atomic_add_f32 v[82:83], v80
.LBB0_1792:
	s_or_b64 exec, exec, s[24:25]
	v_or_b32_e32 v80, 48, v146
	s_waitcnt lgkmcnt(0)
	v_ashrrev_i32_e32 v81, 31, v80
	v_lshlrev_b64 v[82:83], 11, v[80:81]
	v_lshl_add_u64 v[82:83], s[6:7], 0, v[82:83]
	v_lshl_add_u64 v[90:91], v[144:145], 1, v[82:83]
	flat_load_dwordx4 v[82:85], v[90:91]
	flat_load_dwordx4 v[86:89], v[90:91] offset:256
	s_waitcnt vmcnt(0) lgkmcnt(0)
	v_lshlrev_b32_e32 v92, 16, v82
	v_and_b32_e32 v93, 0xffff0000, v82
	v_lshlrev_b32_e32 v82, 16, v83
	v_and_b32_e32 v83, 0xffff0000, v83
	v_lshlrev_b32_e32 v94, 16, v84
	v_and_b32_e32 v95, 0xffff0000, v84
	v_lshlrev_b32_e32 v84, 16, v85
	v_and_b32_e32 v85, 0xffff0000, v85
	v_lshlrev_b32_e32 v96, 16, v86
	v_and_b32_e32 v97, 0xffff0000, v86
	v_lshlrev_b32_e32 v86, 16, v87
	v_and_b32_e32 v87, 0xffff0000, v87
	v_lshlrev_b32_e32 v98, 16, v88
	v_and_b32_e32 v99, 0xffff0000, v88
	v_lshlrev_b32_e32 v88, 16, v89
	v_and_b32_e32 v89, 0xffff0000, v89
	v_pk_add_f32 v[78:79], v[78:79], v[82:83]
	v_pk_add_f32 v[76:77], v[76:77], v[92:93]
	v_pk_add_f32 v[74:75], v[74:75], v[84:85]
	v_pk_add_f32 v[72:73], v[72:73], v[94:95]
	v_pk_add_f32 v[70:71], v[70:71], v[86:87]
	v_pk_add_f32 v[68:69], v[68:69], v[96:97]
	v_pk_add_f32 v[82:83], v[66:67], v[88:89]
	v_pk_add_f32 v[84:85], v[64:65], v[98:99]
	v_cvt_pk_bf16_f32 v64, v76, v77
	v_cvt_pk_bf16_f32 v65, v78, v79
	v_mul_f32_e32 v66, v77, v77
	v_mul_f32_e32 v67, v79, v79
	v_mul_f32_e32 v77, v73, v73
	v_mul_f32_e32 v79, v75, v75
	v_mul_f32_e32 v86, v69, v69
	v_mul_f32_e32 v87, v71, v71
	v_mul_f32_e32 v88, v85, v85
	v_mul_f32_e32 v89, v83, v83
	v_fmac_f32_e32 v66, v76, v76
	v_fmac_f32_e32 v67, v78, v78
	v_fmac_f32_e32 v77, v72, v72
	v_fmac_f32_e32 v79, v74, v74
	v_fmac_f32_e32 v86, v68, v68
	v_fmac_f32_e32 v87, v70, v70
	v_fmac_f32_e32 v88, v84, v84
	v_fmac_f32_e32 v89, v82, v82
	v_add_f32_e32 v66, v66, v67
	v_add_f32_e32 v67, v77, v79
	v_add_f32_e32 v76, v86, v87
	v_add_f32_e32 v77, v88, v89
	v_add_f32_e32 v66, v66, v67
	v_add_f32_e32 v67, v76, v77
	v_add_f32_e32 v76, v66, v67
	v_mov_b32_e32 v77, v76
	v_cvt_pk_bf16_f32 v66, v72, v73
	v_cvt_pk_bf16_f32 v67, v74, v75
	flat_store_dwordx4 v[90:91], v[64:67]
	v_permlane16_swap_b32_e32 v76, v77
	s_nop 0
	v_add_f32_e32 v64, v76, v77
	v_mov_b32_e32 v65, v64
	v_cvt_pk_bf16_f32 v66, v68, v69
	v_cvt_pk_bf16_f32 v67, v70, v71
	v_cvt_pk_bf16_f32 v68, v84, v85
	v_cvt_pk_bf16_f32 v69, v82, v83
	flat_store_dwordx4 v[90:91], v[66:69] offset:256
	v_permlane32_swap_b32_e32 v64, v65
	s_and_saveexec_b64 s[24:25], s[0:1]
	s_cbranch_execz .LBB0_1794
	v_lshl_add_u64 v[66:67], v[80:81], 2, s[10:11]
	s_nop 0
	v_add_f32_e32 v64, v64, v65
	flat_atomic_add_f32 v[66:67], v64
.LBB0_1794:
	s_or_b64 exec, exec, s[24:25]
	v_add_u32_e32 v64, 0x80, v146
	s_waitcnt lgkmcnt(0)
	v_ashrrev_i32_e32 v65, 31, v64
	v_lshlrev_b64 v[66:67], 11, v[64:65]
	v_lshl_add_u64 v[66:67], s[6:7], 0, v[66:67]
	v_lshl_add_u64 v[74:75], v[144:145], 1, v[66:67]
	flat_load_dwordx4 v[66:69], v[74:75]
	flat_load_dwordx4 v[70:73], v[74:75] offset:256
	s_waitcnt vmcnt(0) lgkmcnt(0)
	v_lshlrev_b32_e32 v76, 16, v66
	v_and_b32_e32 v77, 0xffff0000, v66
	v_lshlrev_b32_e32 v66, 16, v67
	v_and_b32_e32 v67, 0xffff0000, v67
	v_lshlrev_b32_e32 v78, 16, v68
	v_and_b32_e32 v79, 0xffff0000, v68
	v_lshlrev_b32_e32 v68, 16, v69
	v_and_b32_e32 v69, 0xffff0000, v69
	v_lshlrev_b32_e32 v80, 16, v70
	v_and_b32_e32 v81, 0xffff0000, v70
	v_lshlrev_b32_e32 v70, 16, v71
	v_and_b32_e32 v71, 0xffff0000, v71
	v_lshlrev_b32_e32 v82, 16, v72
	v_and_b32_e32 v83, 0xffff0000, v72
	v_lshlrev_b32_e32 v72, 16, v73
	v_and_b32_e32 v73, 0xffff0000, v73
	v_pk_add_f32 v[62:63], v[62:63], v[66:67]
	v_pk_add_f32 v[60:61], v[60:61], v[76:77]
	v_pk_add_f32 v[58:59], v[58:59], v[68:69]
	v_pk_add_f32 v[56:57], v[56:57], v[78:79]
	v_pk_add_f32 v[54:55], v[54:55], v[70:71]
	v_pk_add_f32 v[52:53], v[52:53], v[80:81]
	v_pk_add_f32 v[66:67], v[50:51], v[72:73]
	v_pk_add_f32 v[68:69], v[48:49], v[82:83]
	v_cvt_pk_bf16_f32 v48, v60, v61
	v_cvt_pk_bf16_f32 v49, v62, v63
	v_mul_f32_e32 v50, v61, v61
	v_mul_f32_e32 v51, v63, v63
	v_mul_f32_e32 v61, v57, v57
	v_mul_f32_e32 v63, v59, v59
	v_mul_f32_e32 v70, v53, v53
	v_mul_f32_e32 v71, v55, v55
	v_mul_f32_e32 v72, v69, v69
	v_mul_f32_e32 v73, v67, v67
	v_fmac_f32_e32 v50, v60, v60
	v_fmac_f32_e32 v51, v62, v62
	v_fmac_f32_e32 v61, v56, v56
	v_fmac_f32_e32 v63, v58, v58
	v_fmac_f32_e32 v70, v52, v52
	v_fmac_f32_e32 v71, v54, v54
	v_fmac_f32_e32 v72, v68, v68
	v_fmac_f32_e32 v73, v66, v66
	v_add_f32_e32 v50, v50, v51
	v_add_f32_e32 v51, v61, v63
	v_add_f32_e32 v60, v70, v71
	v_add_f32_e32 v61, v72, v73
	v_add_f32_e32 v50, v50, v51
	v_add_f32_e32 v51, v60, v61
	v_add_f32_e32 v60, v50, v51
	v_mov_b32_e32 v61, v60
	v_cvt_pk_bf16_f32 v50, v56, v57
	v_cvt_pk_bf16_f32 v51, v58, v59
	flat_store_dwordx4 v[74:75], v[48:51]
	v_permlane16_swap_b32_e32 v60, v61
	s_nop 0
	v_add_f32_e32 v48, v60, v61
	v_mov_b32_e32 v49, v48
	v_cvt_pk_bf16_f32 v50, v52, v53
	v_cvt_pk_bf16_f32 v51, v54, v55
	v_cvt_pk_bf16_f32 v52, v68, v69
	v_cvt_pk_bf16_f32 v53, v66, v67
	flat_store_dwordx4 v[74:75], v[50:53] offset:256
	v_permlane32_swap_b32_e32 v48, v49
	s_and_saveexec_b64 s[24:25], s[0:1]
	s_cbranch_execz .LBB0_1796
	v_lshl_add_u64 v[50:51], v[64:65], 2, s[10:11]
	s_nop 0
	v_add_f32_e32 v48, v48, v49
	flat_atomic_add_f32 v[50:51], v48
.LBB0_1796:
	s_or_b64 exec, exec, s[24:25]
	v_add_u32_e32 v48, 0x90, v146
	s_waitcnt lgkmcnt(0)
	v_ashrrev_i32_e32 v49, 31, v48
	v_lshlrev_b64 v[50:51], 11, v[48:49]
	v_lshl_add_u64 v[50:51], s[6:7], 0, v[50:51]
	v_lshl_add_u64 v[58:59], v[144:145], 1, v[50:51]
	flat_load_dwordx4 v[50:53], v[58:59]
	flat_load_dwordx4 v[54:57], v[58:59] offset:256
	s_waitcnt vmcnt(0) lgkmcnt(0)
	v_lshlrev_b32_e32 v60, 16, v50
	v_and_b32_e32 v61, 0xffff0000, v50
	v_lshlrev_b32_e32 v50, 16, v51
	v_and_b32_e32 v51, 0xffff0000, v51
	v_lshlrev_b32_e32 v62, 16, v52
	v_and_b32_e32 v63, 0xffff0000, v52
	v_lshlrev_b32_e32 v52, 16, v53
	v_and_b32_e32 v53, 0xffff0000, v53
	v_lshlrev_b32_e32 v64, 16, v54
	v_and_b32_e32 v65, 0xffff0000, v54
	v_lshlrev_b32_e32 v54, 16, v55
	v_and_b32_e32 v55, 0xffff0000, v55
	v_lshlrev_b32_e32 v66, 16, v56
	v_and_b32_e32 v67, 0xffff0000, v56
	v_lshlrev_b32_e32 v56, 16, v57
	v_and_b32_e32 v57, 0xffff0000, v57
	v_pk_add_f32 v[46:47], v[46:47], v[50:51]
	v_pk_add_f32 v[44:45], v[44:45], v[60:61]
	v_pk_add_f32 v[42:43], v[42:43], v[52:53]
	v_pk_add_f32 v[40:41], v[40:41], v[62:63]
	v_pk_add_f32 v[38:39], v[38:39], v[54:55]
	v_pk_add_f32 v[36:37], v[36:37], v[64:65]
	v_pk_add_f32 v[50:51], v[34:35], v[56:57]
	v_pk_add_f32 v[52:53], v[32:33], v[66:67]
	v_cvt_pk_bf16_f32 v32, v44, v45
	v_cvt_pk_bf16_f32 v33, v46, v47
	v_mul_f32_e32 v34, v45, v45
	v_mul_f32_e32 v35, v47, v47
	v_mul_f32_e32 v45, v41, v41
	v_mul_f32_e32 v47, v43, v43
	v_mul_f32_e32 v54, v37, v37
	v_mul_f32_e32 v55, v39, v39
	v_mul_f32_e32 v56, v53, v53
	v_mul_f32_e32 v57, v51, v51
	v_fmac_f32_e32 v34, v44, v44
	v_fmac_f32_e32 v35, v46, v46
	v_fmac_f32_e32 v45, v40, v40
	v_fmac_f32_e32 v47, v42, v42
	v_fmac_f32_e32 v54, v36, v36
	v_fmac_f32_e32 v55, v38, v38
	v_fmac_f32_e32 v56, v52, v52
	v_fmac_f32_e32 v57, v50, v50
	v_add_f32_e32 v34, v34, v35
	v_add_f32_e32 v35, v45, v47
	v_add_f32_e32 v44, v54, v55
	v_add_f32_e32 v45, v56, v57
	v_add_f32_e32 v34, v34, v35
	v_add_f32_e32 v35, v44, v45
	v_add_f32_e32 v44, v34, v35
	v_mov_b32_e32 v45, v44
	v_cvt_pk_bf16_f32 v34, v40, v41
	v_cvt_pk_bf16_f32 v35, v42, v43
	flat_store_dwordx4 v[58:59], v[32:35]
	v_permlane16_swap_b32_e32 v44, v45
	s_nop 0
	v_add_f32_e32 v32, v44, v45
	v_mov_b32_e32 v33, v32
	v_cvt_pk_bf16_f32 v34, v36, v37
	v_cvt_pk_bf16_f32 v35, v38, v39
	v_cvt_pk_bf16_f32 v36, v52, v53
	v_cvt_pk_bf16_f32 v37, v50, v51
	flat_store_dwordx4 v[58:59], v[34:37] offset:256
	v_permlane32_swap_b32_e32 v32, v33
	s_and_saveexec_b64 s[24:25], s[0:1]
	s_cbranch_execz .LBB0_1798
	v_lshl_add_u64 v[34:35], v[48:49], 2, s[10:11]
	s_nop 0
	v_add_f32_e32 v32, v32, v33
	flat_atomic_add_f32 v[34:35], v32
.LBB0_1798:
	s_or_b64 exec, exec, s[24:25]
	v_add_u32_e32 v32, 0xa0, v146
	s_waitcnt lgkmcnt(0)
	v_ashrrev_i32_e32 v33, 31, v32
	v_lshlrev_b64 v[34:35], 11, v[32:33]
	v_lshl_add_u64 v[34:35], s[6:7], 0, v[34:35]
	v_lshl_add_u64 v[42:43], v[144:145], 1, v[34:35]
	flat_load_dwordx4 v[34:37], v[42:43]
	flat_load_dwordx4 v[38:41], v[42:43] offset:256
	s_waitcnt vmcnt(0) lgkmcnt(0)
	v_lshlrev_b32_e32 v44, 16, v34
	v_and_b32_e32 v45, 0xffff0000, v34
	v_lshlrev_b32_e32 v34, 16, v35
	v_and_b32_e32 v35, 0xffff0000, v35
	v_lshlrev_b32_e32 v46, 16, v36
	v_and_b32_e32 v47, 0xffff0000, v36
	v_lshlrev_b32_e32 v36, 16, v37
	v_and_b32_e32 v37, 0xffff0000, v37
	v_lshlrev_b32_e32 v48, 16, v38
	v_and_b32_e32 v49, 0xffff0000, v38
	v_lshlrev_b32_e32 v38, 16, v39
	v_and_b32_e32 v39, 0xffff0000, v39
	v_lshlrev_b32_e32 v50, 16, v40
	v_and_b32_e32 v51, 0xffff0000, v40
	v_lshlrev_b32_e32 v40, 16, v41
	v_and_b32_e32 v41, 0xffff0000, v41
	v_pk_add_f32 v[30:31], v[30:31], v[34:35]
	v_pk_add_f32 v[28:29], v[28:29], v[44:45]
	v_pk_add_f32 v[26:27], v[26:27], v[36:37]
	v_pk_add_f32 v[24:25], v[24:25], v[46:47]
	v_pk_add_f32 v[22:23], v[22:23], v[38:39]
	v_pk_add_f32 v[20:21], v[20:21], v[48:49]
	v_pk_add_f32 v[34:35], v[18:19], v[40:41]
	v_pk_add_f32 v[36:37], v[16:17], v[50:51]
	v_cvt_pk_bf16_f32 v16, v28, v29
	v_cvt_pk_bf16_f32 v17, v30, v31
	v_mul_f32_e32 v18, v29, v29
	v_mul_f32_e32 v19, v31, v31
	v_mul_f32_e32 v29, v25, v25
	v_mul_f32_e32 v31, v27, v27
	v_mul_f32_e32 v38, v21, v21
	v_mul_f32_e32 v39, v23, v23
	v_mul_f32_e32 v40, v37, v37
	v_mul_f32_e32 v41, v35, v35
	v_fmac_f32_e32 v18, v28, v28
	v_fmac_f32_e32 v19, v30, v30
	v_fmac_f32_e32 v29, v24, v24
	v_fmac_f32_e32 v31, v26, v26
	v_fmac_f32_e32 v38, v20, v20
	v_fmac_f32_e32 v39, v22, v22
	v_fmac_f32_e32 v40, v36, v36
	v_fmac_f32_e32 v41, v34, v34
	v_add_f32_e32 v18, v18, v19
	v_add_f32_e32 v19, v29, v31
	v_add_f32_e32 v28, v38, v39
	v_add_f32_e32 v29, v40, v41
	v_add_f32_e32 v18, v18, v19
	v_add_f32_e32 v19, v28, v29
	v_add_f32_e32 v28, v18, v19
	v_mov_b32_e32 v29, v28
	v_cvt_pk_bf16_f32 v18, v24, v25
	v_cvt_pk_bf16_f32 v19, v26, v27
	flat_store_dwordx4 v[42:43], v[16:19]
	v_permlane16_swap_b32_e32 v28, v29
	s_nop 0
	v_add_f32_e32 v16, v28, v29
	v_mov_b32_e32 v17, v16
	v_cvt_pk_bf16_f32 v18, v20, v21
	v_cvt_pk_bf16_f32 v19, v22, v23
	v_cvt_pk_bf16_f32 v20, v36, v37
	v_cvt_pk_bf16_f32 v21, v34, v35
	flat_store_dwordx4 v[42:43], v[18:21] offset:256
	v_permlane32_swap_b32_e32 v16, v17
	s_and_saveexec_b64 s[24:25], s[0:1]
	s_cbranch_execz .LBB0_1800
	v_lshl_add_u64 v[18:19], v[32:33], 2, s[10:11]
	s_nop 0
	v_add_f32_e32 v16, v16, v17
	flat_atomic_add_f32 v[18:19], v16
.LBB0_1800:
	s_or_b64 exec, exec, s[24:25]
	v_add_u32_e32 v16, 0xb0, v146
	s_waitcnt lgkmcnt(0)
	v_ashrrev_i32_e32 v17, 31, v16
	v_lshlrev_b64 v[18:19], 11, v[16:17]
	v_lshl_add_u64 v[18:19], s[6:7], 0, v[18:19]
	v_lshl_add_u64 v[26:27], v[144:145], 1, v[18:19]
	flat_load_dwordx4 v[18:21], v[26:27]
	flat_load_dwordx4 v[22:25], v[26:27] offset:256
	s_waitcnt vmcnt(0) lgkmcnt(0)
	v_lshlrev_b32_e32 v28, 16, v18
	v_and_b32_e32 v29, 0xffff0000, v18
	v_lshlrev_b32_e32 v18, 16, v19
	v_and_b32_e32 v19, 0xffff0000, v19
	v_lshlrev_b32_e32 v30, 16, v20
	v_and_b32_e32 v31, 0xffff0000, v20
	v_lshlrev_b32_e32 v20, 16, v21
	v_and_b32_e32 v21, 0xffff0000, v21
	v_lshlrev_b32_e32 v32, 16, v22
	v_and_b32_e32 v33, 0xffff0000, v22
	v_lshlrev_b32_e32 v22, 16, v23
	v_and_b32_e32 v23, 0xffff0000, v23
	v_lshlrev_b32_e32 v34, 16, v24
	v_and_b32_e32 v35, 0xffff0000, v24
	v_lshlrev_b32_e32 v24, 16, v25
	v_and_b32_e32 v25, 0xffff0000, v25
	v_pk_add_f32 v[14:15], v[14:15], v[18:19]
	v_pk_add_f32 v[12:13], v[12:13], v[28:29]
	v_pk_add_f32 v[10:11], v[10:11], v[20:21]
	v_pk_add_f32 v[8:9], v[8:9], v[30:31]
	v_pk_add_f32 v[6:7], v[6:7], v[22:23]
	v_pk_add_f32 v[4:5], v[4:5], v[32:33]
	v_pk_add_f32 v[18:19], v[2:3], v[24:25]
	v_pk_add_f32 v[20:21], v[0:1], v[34:35]
	v_cvt_pk_bf16_f32 v0, v12, v13
	v_cvt_pk_bf16_f32 v1, v14, v15
	v_mul_f32_e32 v2, v13, v13
	v_mul_f32_e32 v3, v15, v15
	v_mul_f32_e32 v13, v9, v9
	v_mul_f32_e32 v15, v11, v11
	v_mul_f32_e32 v22, v5, v5
	v_mul_f32_e32 v23, v7, v7
	v_mul_f32_e32 v24, v21, v21
	v_mul_f32_e32 v25, v19, v19
	v_fmac_f32_e32 v2, v12, v12
	v_fmac_f32_e32 v3, v14, v14
	v_fmac_f32_e32 v13, v8, v8
	v_fmac_f32_e32 v15, v10, v10
	v_fmac_f32_e32 v22, v4, v4
	v_fmac_f32_e32 v23, v6, v6
	v_fmac_f32_e32 v24, v20, v20
	v_fmac_f32_e32 v25, v18, v18
	v_add_f32_e32 v2, v2, v3
	v_add_f32_e32 v3, v13, v15
	v_add_f32_e32 v12, v22, v23
	v_add_f32_e32 v13, v24, v25
	v_add_f32_e32 v2, v2, v3
	v_add_f32_e32 v3, v12, v13
	v_add_f32_e32 v12, v2, v3
	v_mov_b32_e32 v13, v12
	v_cvt_pk_bf16_f32 v2, v8, v9
	v_cvt_pk_bf16_f32 v3, v10, v11
	flat_store_dwordx4 v[26:27], v[0:3]
	v_permlane16_swap_b32_e32 v12, v13
	s_nop 0
	v_add_f32_e32 v0, v12, v13
	v_mov_b32_e32 v1, v0
	v_cvt_pk_bf16_f32 v2, v4, v5
	v_cvt_pk_bf16_f32 v3, v6, v7
	v_cvt_pk_bf16_f32 v4, v20, v21
	v_cvt_pk_bf16_f32 v5, v18, v19
	flat_store_dwordx4 v[26:27], v[2:5] offset:256
	v_permlane32_swap_b32_e32 v0, v1
	s_and_saveexec_b64 s[24:25], s[0:1]
	s_cbranch_execz .LBB0_1802
	v_lshl_add_u64 v[2:3], v[16:17], 2, s[10:11]
	s_nop 0
	v_add_f32_e32 v0, v0, v1
	flat_atomic_add_f32 v[2:3], v0
